# GEMM K-loops: flips deleted, static s_setprio 1 for waves 0-3 instead (other half)
# baseline (speedup 1.0000x reference)
.LBB0_168:
	s_ashr_i32 s13, s12, 31
	s_lshl_b64 s[20:21], s[12:13], 20
	s_add_u32 s20, s0, s20
	s_addc_u32 s21, s1, s21
	s_and_b64 s[22:23], s[38:39], exec
	s_cselect_b32 s13, s21, s41
	s_cselect_b32 s47, s20, s40
	s_ashr_i32 s11, s10, 31
	s_lshl_b64 s[22:23], s[10:11], 20
	s_add_u32 s22, s2, s22
	s_addc_u32 s23, s4, s23
	s_and_b64 s[44:45], s[38:39], exec
	s_cselect_b32 s11, s23, s43
	s_cselect_b32 s48, s22, s42
	s_add_u32 s40, s40, 0x80080
	s_addc_u32 s41, s41, 0
	s_add_u32 s49, s42, 0x100
	v_mov_b32_e32 v2, 0
	s_addc_u32 s50, s43, 0
	s_mov_b32 s51, -2
	v_mov_b32_e32 v3, v2
	v_mov_b32_e32 v4, v2
	v_mov_b32_e32 v5, v2
	v_mov_b32_e32 v6, v2
	v_mov_b32_e32 v7, v2
	v_mov_b32_e32 v8, v2
	v_mov_b32_e32 v9, v2
	v_mov_b32_e32 v10, v2
	v_mov_b32_e32 v11, v2
	v_mov_b32_e32 v12, v2
	v_mov_b32_e32 v13, v2
	v_mov_b32_e32 v18, v2
	v_mov_b32_e32 v19, v2
	v_mov_b32_e32 v20, v2
	v_mov_b32_e32 v21, v2
	v_mov_b32_e32 v26, v2
	v_mov_b32_e32 v27, v2
	v_mov_b32_e32 v28, v2
	v_mov_b32_e32 v29, v2
	v_mov_b32_e32 v34, v2
	v_mov_b32_e32 v35, v2
	v_mov_b32_e32 v36, v2
	v_mov_b32_e32 v37, v2
	v_mov_b32_e32 v42, v2
	v_mov_b32_e32 v43, v2
	v_mov_b32_e32 v44, v2
	v_mov_b32_e32 v45, v2
	v_mov_b32_e32 v50, v2
	v_mov_b32_e32 v51, v2
	v_mov_b32_e32 v52, v2
	v_mov_b32_e32 v53, v2
	v_mov_b32_e32 v14, v2
	v_mov_b32_e32 v15, v2
	v_mov_b32_e32 v16, v2
	v_mov_b32_e32 v17, v2
	v_mov_b32_e32 v22, v2
	v_mov_b32_e32 v23, v2
	v_mov_b32_e32 v24, v2
	v_mov_b32_e32 v25, v2
	v_mov_b32_e32 v30, v2
	v_mov_b32_e32 v31, v2
	v_mov_b32_e32 v32, v2
	v_mov_b32_e32 v33, v2
	v_mov_b32_e32 v38, v2
	v_mov_b32_e32 v39, v2
	v_mov_b32_e32 v40, v2
	v_mov_b32_e32 v41, v2
	v_mov_b32_e32 v46, v2
	v_mov_b32_e32 v47, v2
	v_mov_b32_e32 v48, v2
	v_mov_b32_e32 v49, v2
	v_mov_b32_e32 v54, v2
	v_mov_b32_e32 v55, v2
	v_mov_b32_e32 v56, v2
	v_mov_b32_e32 v57, v2
	v_mov_b32_e32 v58, v2
	v_mov_b32_e32 v59, v2
	v_mov_b32_e32 v60, v2
	v_mov_b32_e32 v61, v2
	v_mov_b32_e32 v62, v2
	v_mov_b32_e32 v63, v2
	v_mov_b32_e32 v64, v2
	v_mov_b32_e32 v65, v2
	v_mov_b32_e32 v66, v2
	v_mov_b32_e32 v67, v2
	v_mov_b32_e32 v68, v2
	v_mov_b32_e32 v69, v2
	v_mov_b32_e32 v70, v2
	v_mov_b32_e32 v71, v2
	v_mov_b32_e32 v72, v2
	v_mov_b32_e32 v73, v2
	v_mov_b32_e32 v74, v2
	v_mov_b32_e32 v75, v2
	v_mov_b32_e32 v76, v2
	v_mov_b32_e32 v77, v2
	v_mov_b32_e32 v82, v2
	v_mov_b32_e32 v83, v2
	v_mov_b32_e32 v84, v2
	v_mov_b32_e32 v85, v2
	v_mov_b32_e32 v90, v2
	v_mov_b32_e32 v91, v2
	v_mov_b32_e32 v92, v2
	v_mov_b32_e32 v93, v2
	v_mov_b32_e32 v98, v2
	v_mov_b32_e32 v99, v2
	v_mov_b32_e32 v100, v2
	v_mov_b32_e32 v101, v2
	v_mov_b32_e32 v106, v2
	v_mov_b32_e32 v107, v2
	v_mov_b32_e32 v108, v2
	v_mov_b32_e32 v109, v2
	v_mov_b32_e32 v114, v2
	v_mov_b32_e32 v115, v2
	v_mov_b32_e32 v116, v2
	v_mov_b32_e32 v117, v2
	v_mov_b32_e32 v78, v2
	v_mov_b32_e32 v79, v2
	v_mov_b32_e32 v80, v2
	v_mov_b32_e32 v81, v2
	v_mov_b32_e32 v86, v2
	v_mov_b32_e32 v87, v2
	v_mov_b32_e32 v88, v2
	v_mov_b32_e32 v89, v2
	v_mov_b32_e32 v94, v2
	v_mov_b32_e32 v95, v2
	v_mov_b32_e32 v96, v2
	v_mov_b32_e32 v97, v2
	v_mov_b32_e32 v102, v2
	v_mov_b32_e32 v103, v2
	v_mov_b32_e32 v104, v2
	v_mov_b32_e32 v105, v2
	v_mov_b32_e32 v110, v2
	v_mov_b32_e32 v111, v2
	v_mov_b32_e32 v112, v2
	v_mov_b32_e32 v113, v2
	v_mov_b32_e32 v118, v2
	v_mov_b32_e32 v119, v2
	v_mov_b32_e32 v120, v2
	v_mov_b32_e32 v121, v2
	v_mov_b32_e32 v122, v2
	v_mov_b32_e32 v123, v2
	v_mov_b32_e32 v124, v2
	v_mov_b32_e32 v125, v2
	v_mov_b32_e32 v126, v2
	v_mov_b32_e32 v127, v2
	v_mov_b32_e32 v128, v2
	v_mov_b32_e32 v129, v2
	v_readfirstlane_b32 s98, v146
	s_nop 3
	s_lshr_b32 s98, s98, 6
	s_cmp_lt_u32 s98, 4
	s_cbranch_scc0 .Lgprio0
	s_setprio 1

.LBB0_515:
	s_ashr_i32 s21, s20, 31
	s_lshl_b64 s[22:23], s[20:21], 20
	s_add_u32 s22, s0, s22
	s_addc_u32 s23, s1, s23
	s_and_b64 s[42:43], s[40:41], exec
	s_cselect_b32 s21, s23, s45
	s_cselect_b32 s50, s22, s44
	s_ashr_i32 s13, s12, 31
	s_lshl_b64 s[42:43], s[12:13], 20
	s_add_u32 s42, s2, s42
	s_addc_u32 s43, s4, s43
	s_and_b64 s[48:49], s[40:41], exec
	s_cselect_b32 s13, s43, s47
	s_cselect_b32 s51, s42, s46
	s_add_u32 s44, s44, 0x80080
	s_addc_u32 s45, s45, 0
	s_add_u32 s55, s46, 0x100
	v_mov_b32_e32 v2, 0
	s_addc_u32 s56, s47, 0
	s_mov_b32 s57, -2
	s_waitcnt lgkmcnt(0)
	v_mov_b32_e32 v3, v2
	v_mov_b32_e32 v4, v2
	v_mov_b32_e32 v5, v2
	v_mov_b32_e32 v6, v2
	v_mov_b32_e32 v7, v2
	v_mov_b32_e32 v8, v2
	v_mov_b32_e32 v9, v2
	v_mov_b32_e32 v18, v2
	v_mov_b32_e32 v19, v2
	v_mov_b32_e32 v20, v2
	v_mov_b32_e32 v21, v2
	v_mov_b32_e32 v22, v2
	v_mov_b32_e32 v23, v2
	v_mov_b32_e32 v24, v2
	v_mov_b32_e32 v25, v2
	v_mov_b32_e32 v34, v2
	v_mov_b32_e32 v35, v2
	v_mov_b32_e32 v36, v2
	v_mov_b32_e32 v37, v2
	v_mov_b32_e32 v38, v2
	v_mov_b32_e32 v39, v2
	v_mov_b32_e32 v40, v2
	v_mov_b32_e32 v41, v2
	v_mov_b32_e32 v50, v2
	v_mov_b32_e32 v51, v2
	v_mov_b32_e32 v52, v2
	v_mov_b32_e32 v53, v2
	v_mov_b32_e32 v54, v2
	v_mov_b32_e32 v55, v2
	v_mov_b32_e32 v56, v2
	v_mov_b32_e32 v57, v2
	v_mov_b32_e32 v10, v2
	v_mov_b32_e32 v11, v2
	v_mov_b32_e32 v12, v2
	v_mov_b32_e32 v13, v2
	v_mov_b32_e32 v14, v2
	v_mov_b32_e32 v15, v2
	v_mov_b32_e32 v16, v2
	v_mov_b32_e32 v17, v2
	v_mov_b32_e32 v26, v2
	v_mov_b32_e32 v27, v2
	v_mov_b32_e32 v28, v2
	v_mov_b32_e32 v29, v2
	v_mov_b32_e32 v30, v2
	v_mov_b32_e32 v31, v2
	v_mov_b32_e32 v32, v2
	v_mov_b32_e32 v33, v2
	v_mov_b32_e32 v42, v2
	v_mov_b32_e32 v43, v2
	v_mov_b32_e32 v44, v2
	v_mov_b32_e32 v45, v2
	v_mov_b32_e32 v46, v2
	v_mov_b32_e32 v47, v2
	v_mov_b32_e32 v48, v2
	v_mov_b32_e32 v49, v2
	v_mov_b32_e32 v58, v2
	v_mov_b32_e32 v59, v2
	v_mov_b32_e32 v60, v2
	v_mov_b32_e32 v61, v2
	v_mov_b32_e32 v62, v2
	v_mov_b32_e32 v63, v2
	v_mov_b32_e32 v64, v2
	v_mov_b32_e32 v65, v2
	v_mov_b32_e32 v66, v2
	v_mov_b32_e32 v67, v2
	v_mov_b32_e32 v68, v2
	v_mov_b32_e32 v69, v2
	v_mov_b32_e32 v70, v2
	v_mov_b32_e32 v71, v2
	v_mov_b32_e32 v72, v2
	v_mov_b32_e32 v73, v2
	v_mov_b32_e32 v90, v2
	v_mov_b32_e32 v91, v2
	v_mov_b32_e32 v92, v2
	v_mov_b32_e32 v93, v2
	v_mov_b32_e32 v94, v2
	v_mov_b32_e32 v95, v2
	v_mov_b32_e32 v96, v2
	v_mov_b32_e32 v97, v2
	v_mov_b32_e32 v114, v2
	v_mov_b32_e32 v115, v2
	v_mov_b32_e32 v116, v2
	v_mov_b32_e32 v117, v2
	v_mov_b32_e32 v118, v2
	v_mov_b32_e32 v119, v2
	v_mov_b32_e32 v120, v2
	v_mov_b32_e32 v121, v2
	v_mov_b32_e32 v130, v2
	v_mov_b32_e32 v131, v2
	v_mov_b32_e32 v132, v2
	v_mov_b32_e32 v133, v2
	v_mov_b32_e32 v134, v2
	v_mov_b32_e32 v135, v2
	v_mov_b32_e32 v136, v2
	v_mov_b32_e32 v137, v2
	v_mov_b32_e32 v74, v2
	v_mov_b32_e32 v75, v2
	v_mov_b32_e32 v76, v2
	v_mov_b32_e32 v77, v2
	v_mov_b32_e32 v78, v2
	v_mov_b32_e32 v79, v2
	v_mov_b32_e32 v80, v2
	v_mov_b32_e32 v81, v2
	v_mov_b32_e32 v106, v2
	v_mov_b32_e32 v107, v2
	v_mov_b32_e32 v108, v2
	v_mov_b32_e32 v109, v2
	v_mov_b32_e32 v110, v2
	v_mov_b32_e32 v111, v2
	v_mov_b32_e32 v112, v2
	v_mov_b32_e32 v113, v2
	v_mov_b32_e32 v122, v2
	v_mov_b32_e32 v123, v2
	v_mov_b32_e32 v124, v2
	v_mov_b32_e32 v125, v2
	v_mov_b32_e32 v126, v2
	v_mov_b32_e32 v127, v2
	v_mov_b32_e32 v128, v2
	v_mov_b32_e32 v129, v2
	v_mov_b32_e32 v138, v2
	v_mov_b32_e32 v139, v2
	v_mov_b32_e32 v140, v2
	v_mov_b32_e32 v141, v2
	v_mov_b32_e32 v142, v2
	v_mov_b32_e32 v143, v2
	v_mov_b32_e32 v144, v2
	v_mov_b32_e32 v145, v2
	v_readfirstlane_b32 s98, v146
	s_nop 3
	s_lshr_b32 s98, s98, 6
	s_cmp_lt_u32 s98, 4
	s_cbranch_scc0 .Lgprio1
	s_setprio 1

.LBB0_603:
	s_ashr_i32 s41, s40, 31
	s_lshl_b64 s[18:19], s[40:41], 20
	s_add_u32 s42, s0, s18
	s_addc_u32 s43, s1, s19
	s_and_b64 s[18:19], s[38:39], exec
	s_cselect_b32 s18, s43, s7
	s_cselect_b32 s19, s42, s6
	s_ashr_i32 s21, s20, 31
	s_lshl_b64 s[44:45], s[20:21], 20
	s_add_u32 s44, s2, s44
	s_addc_u32 s45, s14, s45
	s_and_b64 s[46:47], s[38:39], exec
	s_cselect_b32 s21, s45, s23
	s_cselect_b32 s25, s44, s22
	s_add_u32 s6, s6, 0x80080
	s_addc_u32 s7, s7, 0
	s_add_u32 s41, s22, 0x100
	v_mov_b32_e32 v2, 0
	s_addc_u32 s52, s23, 0
	s_mov_b32 s53, -2
	v_mov_b32_e32 v3, v2
	v_mov_b32_e32 v4, v2
	v_mov_b32_e32 v5, v2
	v_mov_b32_e32 v6, v2
	v_mov_b32_e32 v7, v2
	v_mov_b32_e32 v8, v2
	v_mov_b32_e32 v9, v2
	v_mov_b32_e32 v18, v2
	v_mov_b32_e32 v19, v2
	v_mov_b32_e32 v20, v2
	v_mov_b32_e32 v21, v2
	v_mov_b32_e32 v22, v2
	v_mov_b32_e32 v23, v2
	v_mov_b32_e32 v24, v2
	v_mov_b32_e32 v25, v2
	v_mov_b32_e32 v34, v2
	v_mov_b32_e32 v35, v2
	v_mov_b32_e32 v36, v2
	v_mov_b32_e32 v37, v2
	v_mov_b32_e32 v38, v2
	v_mov_b32_e32 v39, v2
	v_mov_b32_e32 v40, v2
	v_mov_b32_e32 v41, v2
	v_mov_b32_e32 v50, v2
	v_mov_b32_e32 v51, v2
	v_mov_b32_e32 v52, v2
	v_mov_b32_e32 v53, v2
	v_mov_b32_e32 v54, v2
	v_mov_b32_e32 v55, v2
	v_mov_b32_e32 v56, v2
	v_mov_b32_e32 v57, v2
	v_mov_b32_e32 v10, v2
	v_mov_b32_e32 v11, v2
	v_mov_b32_e32 v12, v2
	v_mov_b32_e32 v13, v2
	v_mov_b32_e32 v14, v2
	v_mov_b32_e32 v15, v2
	v_mov_b32_e32 v16, v2
	v_mov_b32_e32 v17, v2
	v_mov_b32_e32 v26, v2
	v_mov_b32_e32 v27, v2
	v_mov_b32_e32 v28, v2
	v_mov_b32_e32 v29, v2
	v_mov_b32_e32 v30, v2
	v_mov_b32_e32 v31, v2
	v_mov_b32_e32 v32, v2
	v_mov_b32_e32 v33, v2
	v_mov_b32_e32 v42, v2
	v_mov_b32_e32 v43, v2
	v_mov_b32_e32 v44, v2
	v_mov_b32_e32 v45, v2
	v_mov_b32_e32 v46, v2
	v_mov_b32_e32 v47, v2
	v_mov_b32_e32 v48, v2
	v_mov_b32_e32 v49, v2
	v_mov_b32_e32 v58, v2
	v_mov_b32_e32 v59, v2
	v_mov_b32_e32 v60, v2
	v_mov_b32_e32 v61, v2
	v_mov_b32_e32 v62, v2
	v_mov_b32_e32 v63, v2
	v_mov_b32_e32 v64, v2
	v_mov_b32_e32 v65, v2
	v_mov_b32_e32 v66, v2
	v_mov_b32_e32 v67, v2
	v_mov_b32_e32 v68, v2
	v_mov_b32_e32 v69, v2
	v_mov_b32_e32 v70, v2
	v_mov_b32_e32 v71, v2
	v_mov_b32_e32 v72, v2
	v_mov_b32_e32 v73, v2
	v_mov_b32_e32 v82, v2
	v_mov_b32_e32 v83, v2
	v_mov_b32_e32 v84, v2
	v_mov_b32_e32 v85, v2
	v_mov_b32_e32 v86, v2
	v_mov_b32_e32 v87, v2
	v_mov_b32_e32 v88, v2
	v_mov_b32_e32 v89, v2
	v_mov_b32_e32 v98, v2
	v_mov_b32_e32 v99, v2
	v_mov_b32_e32 v100, v2
	v_mov_b32_e32 v101, v2
	v_mov_b32_e32 v102, v2
	v_mov_b32_e32 v103, v2
	v_mov_b32_e32 v104, v2
	v_mov_b32_e32 v105, v2
	v_mov_b32_e32 v114, v2
	v_mov_b32_e32 v115, v2
	v_mov_b32_e32 v116, v2
	v_mov_b32_e32 v117, v2
	v_mov_b32_e32 v118, v2
	v_mov_b32_e32 v119, v2
	v_mov_b32_e32 v120, v2
	v_mov_b32_e32 v121, v2
	v_mov_b32_e32 v74, v2
	v_mov_b32_e32 v75, v2
	v_mov_b32_e32 v76, v2
	v_mov_b32_e32 v77, v2
	v_mov_b32_e32 v78, v2
	v_mov_b32_e32 v79, v2
	v_mov_b32_e32 v80, v2
	v_mov_b32_e32 v81, v2
	v_mov_b32_e32 v90, v2
	v_mov_b32_e32 v91, v2
	v_mov_b32_e32 v92, v2
	v_mov_b32_e32 v93, v2
	v_mov_b32_e32 v94, v2
	v_mov_b32_e32 v95, v2
	v_mov_b32_e32 v96, v2
	v_mov_b32_e32 v97, v2
	v_mov_b32_e32 v106, v2
	v_mov_b32_e32 v107, v2
	v_mov_b32_e32 v108, v2
	v_mov_b32_e32 v109, v2
	v_mov_b32_e32 v110, v2
	v_mov_b32_e32 v111, v2
	v_mov_b32_e32 v112, v2
	v_mov_b32_e32 v113, v2
	v_mov_b32_e32 v122, v2
	v_mov_b32_e32 v123, v2
	v_mov_b32_e32 v124, v2
	v_mov_b32_e32 v125, v2
	v_mov_b32_e32 v126, v2
	v_mov_b32_e32 v127, v2
	v_mov_b32_e32 v128, v2
	v_mov_b32_e32 v129, v2
	v_readfirstlane_b32 s98, v146
	s_nop 3
	s_lshr_b32 s98, s98, 6
	s_cmp_lt_u32 s98, 4
	s_cbranch_scc0 .Lgprio2
	s_setprio 1

.LBB0_727:
	s_add_u32 s18, s46, 0x100
	v_mov_b32_e32 v2, 0
	s_addc_u32 s19, s47, 0
	s_mov_b32 s25, -2
	v_mov_b32_e32 v3, v2
	v_mov_b32_e32 v4, v2
	v_mov_b32_e32 v5, v2
	v_mov_b32_e32 v6, v2
	v_mov_b32_e32 v7, v2
	v_mov_b32_e32 v8, v2
	v_mov_b32_e32 v9, v2
	v_mov_b32_e32 v18, v2
	v_mov_b32_e32 v19, v2
	v_mov_b32_e32 v20, v2
	v_mov_b32_e32 v21, v2
	v_mov_b32_e32 v22, v2
	v_mov_b32_e32 v23, v2
	v_mov_b32_e32 v24, v2
	v_mov_b32_e32 v25, v2
	v_mov_b32_e32 v34, v2
	v_mov_b32_e32 v35, v2
	v_mov_b32_e32 v36, v2
	v_mov_b32_e32 v37, v2
	v_mov_b32_e32 v38, v2
	v_mov_b32_e32 v39, v2
	v_mov_b32_e32 v40, v2
	v_mov_b32_e32 v41, v2
	v_mov_b32_e32 v66, v2
	v_mov_b32_e32 v67, v2
	v_mov_b32_e32 v68, v2
	v_mov_b32_e32 v69, v2
	v_mov_b32_e32 v70, v2
	v_mov_b32_e32 v71, v2
	v_mov_b32_e32 v72, v2
	v_mov_b32_e32 v73, v2
	v_mov_b32_e32 v10, v2
	s_waitcnt lgkmcnt(0)
	v_mov_b32_e32 v11, v2
	v_mov_b32_e32 v12, v2
	v_mov_b32_e32 v13, v2
	v_mov_b32_e32 v14, v2
	v_mov_b32_e32 v15, v2
	v_mov_b32_e32 v16, v2
	v_mov_b32_e32 v17, v2
	v_mov_b32_e32 v26, v2
	v_mov_b32_e32 v27, v2
	v_mov_b32_e32 v28, v2
	v_mov_b32_e32 v29, v2
	v_mov_b32_e32 v30, v2
	v_mov_b32_e32 v31, v2
	v_mov_b32_e32 v32, v2
	v_mov_b32_e32 v33, v2
	v_mov_b32_e32 v58, v2
	v_mov_b32_e32 v59, v2
	v_mov_b32_e32 v60, v2
	v_mov_b32_e32 v61, v2
	v_mov_b32_e32 v62, v2
	v_mov_b32_e32 v63, v2
	v_mov_b32_e32 v64, v2
	v_mov_b32_e32 v65, v2
	v_mov_b32_e32 v74, v2
	v_mov_b32_e32 v75, v2
	v_mov_b32_e32 v76, v2
	v_mov_b32_e32 v77, v2
	v_mov_b32_e32 v78, v2
	v_mov_b32_e32 v79, v2
	v_mov_b32_e32 v80, v2
	v_mov_b32_e32 v81, v2
	v_mov_b32_e32 v82, v2
	v_mov_b32_e32 v83, v2
	v_mov_b32_e32 v84, v2
	v_mov_b32_e32 v85, v2
	v_mov_b32_e32 v86, v2
	v_mov_b32_e32 v87, v2
	v_mov_b32_e32 v88, v2
	v_mov_b32_e32 v89, v2
	v_mov_b32_e32 v98, v2
	v_mov_b32_e32 v99, v2
	v_mov_b32_e32 v100, v2
	v_mov_b32_e32 v101, v2
	v_mov_b32_e32 v102, v2
	v_mov_b32_e32 v103, v2
	v_mov_b32_e32 v104, v2
	v_mov_b32_e32 v105, v2
	v_mov_b32_e32 v114, v2
	v_mov_b32_e32 v115, v2
	v_mov_b32_e32 v116, v2
	v_mov_b32_e32 v117, v2
	v_mov_b32_e32 v118, v2
	v_mov_b32_e32 v119, v2
	v_mov_b32_e32 v120, v2
	v_mov_b32_e32 v121, v2
	v_mov_b32_e32 v130, v2
	v_mov_b32_e32 v131, v2
	v_mov_b32_e32 v132, v2
	v_mov_b32_e32 v133, v2
	v_mov_b32_e32 v134, v2
	v_mov_b32_e32 v135, v2
	v_mov_b32_e32 v136, v2
	v_mov_b32_e32 v137, v2
	v_mov_b32_e32 v90, v2
	v_mov_b32_e32 v91, v2
	v_mov_b32_e32 v92, v2
	v_mov_b32_e32 v93, v2
	v_mov_b32_e32 v94, v2
	v_mov_b32_e32 v95, v2
	v_mov_b32_e32 v96, v2
	v_mov_b32_e32 v97, v2
	v_mov_b32_e32 v106, v2
	v_mov_b32_e32 v107, v2
	v_mov_b32_e32 v108, v2
	v_mov_b32_e32 v109, v2
	v_mov_b32_e32 v110, v2
	v_mov_b32_e32 v111, v2
	v_mov_b32_e32 v112, v2
	v_mov_b32_e32 v113, v2
	v_mov_b32_e32 v122, v2
	v_mov_b32_e32 v123, v2
	v_mov_b32_e32 v124, v2
	v_mov_b32_e32 v125, v2
	v_mov_b32_e32 v126, v2
	v_mov_b32_e32 v127, v2
	v_mov_b32_e32 v128, v2
	v_mov_b32_e32 v129, v2
	v_mov_b32_e32 v138, v2
	v_mov_b32_e32 v139, v2
	v_mov_b32_e32 v140, v2
	v_mov_b32_e32 v141, v2
	v_mov_b32_e32 v142, v2
	v_mov_b32_e32 v143, v2
	v_mov_b32_e32 v144, v2
	v_mov_b32_e32 v145, v2
	v_readfirstlane_b32 s98, v146
	s_nop 3
	s_lshr_b32 s98, s98, 6
	s_cmp_lt_u32 s98, 4
	s_cbranch_scc0 .Lgprio3
	s_setprio 1
